# attention loop: QK MFMAs start after three PV MFMAs (one slot later than v177); otherwise as v177
# speedup vs baseline: 1.0040x; 1.0040x over previous
; template <int KS> __device__ __forceinline__ void pv_ks(f32x16* o, int vb, bf16x8 pa) {
;     const s16x4 l0 = tr_read<v_rd_off(0, KS, 0)>(vb), h0 = tr_read<v_rd_off(0, KS, 1)>(vb), l1 = tr_read<v_rd_off(1, KS, 0)>(vb), h1 = tr_read<v_rd_off(1, KS, 1)>(vb);
;     const s16x4 l2 = tr_read<v_rd_off(2, KS, 0)>(vb), h2 = tr_read<v_rd_off(2, KS, 1)>(vb), l3 = tr_read<v_rd_off(3, KS, 0)>(vb), h3 = tr_read<v_rd_off(3, KS, 1)>(vb);
;     ...
;     asm volatile("s_waitcnt lgkmcnt(6)" ::: "memory"); SBAR();
;     o[0] = __builtin_amdgcn_mfma_f32_32x32x16_bf16(pa, PK(l0, h0), o[0], 0, 0, 0);
;     asm volatile("s_waitcnt lgkmcnt(4)" ::: "memory"); SBAR();
;     o[1] = __builtin_amdgcn_mfma_f32_32x32x16_bf16(pa, PK(l1, h1), o[1], 0, 0, 0);
;     asm volatile("s_waitcnt lgkmcnt(2)" ::: "memory"); SBAR();
;     o[2] = __builtin_amdgcn_mfma_f32_32x32x16_bf16(pa, PK(l2, h2), o[2], 0, 0, 0);
;     asm volatile("s_waitcnt lgkmcnt(0)" ::: "memory"); SBAR();
;     o[3] = __builtin_amdgcn_mfma_f32_32x32x16_bf16(pa, PK(l3, h3), o[3], 0, 0, 0);
;     ...
; }
; __device__ __forceinline__ void pv_d0(f32x16* o, int vb, bf16x8 pa0, bf16x8 pa1, bf16x8 pa2, bf16x8 pa3) {
;     __builtin_amdgcn_s_setprio(1);
;     pv_ks<0>(o, vb, pa0); pv_ks<1>(o, vb, pa1); pv_ks<2>(o, vb, pa2); pv_ks<3>(o, vb, pa3);
;     __builtin_amdgcn_s_setprio(0);
; }
; __device__ __forceinline__ void exp_half(f32x16& p) {
; #pragma unroll
;     for (int r = 0; r < 16; ++r) p[r] = __builtin_amdgcn_exp2f(p[r]);
; }
; __device__ __forceinline__ void pack_p(const f32x16& p0, const f32x16& p1, float& l_reg, bf16x8& pa0, bf16x8& pa1, bf16x8& pa2, bf16x8& pa3) {
;     float ps = 0;
; #pragma unroll
;     for (int r = 0; r < 16; ++r) ps += p0[r];
; #pragma unroll
;     for (int r = 0; r < 16; ++r) ps += p1[r];
;     l_reg += ps;
;     ...
;     PK4(p0, 0, pa0); PK4(p0, 8, pa1); PK4(p1, 0, pa2); PK4(p1, 8, pa3);
;     ...
; }
; template <int ND0> __device__ __forceinline__ void qkt(f32x16& p0, f32x16& p1, const char* Ks, const bf16x8* qr, int r32, int hi, int colB0) {
; #pragma unroll
;     for (int d0 = 0; d0 < ND0; ++d0) { const int cb = colB0 + (d0 * 16 + hi * 8) * 2;
;         const bf16x8 b0 = *reinterpret_cast<const bf16x8*>(Ks + KSWZ(r32, cb));
;         const bf16x8 b1 = *reinterpret_cast<const bf16x8*>(Ks + KSWZ(32 + r32, cb));
;         p0 = __builtin_amdgcn_mfma_f32_32x32x16_bf16(b0, qr[d0], p0, 0, 0, 0);
.Lsym_nostage_s0:
	s_waitcnt lgkmcnt(14)
	v_mfma_f32_32x32x16_bf16 v[48:63], v[128:131], v[144:147], v[48:63]
	ds_read_b64_tr_b16 v[144:145], v252 offset:4096
	ds_read_b64_tr_b16 v[146:147], v252 offset:6144
	v_exp_f32_e32 v88, v88
	v_exp_f32_e32 v89, v89
	v_exp_f32_e32 v90, v90
	s_waitcnt lgkmcnt(14)
	v_mfma_f32_32x32x16_bf16 v[32:47], v[128:131], v[148:151], v[32:47]
	ds_read_b64_tr_b16 v[148:149], v252 offset:4608
	ds_read_b64_tr_b16 v[150:151], v252 offset:6656
	v_exp_f32_e32 v91, v91
	v_add_f32_e32 v182, v88, v182
	v_add_f32_e32 v182, v89, v182
	v_cvt_pk_bf16_f32 v132, v88, v89
	v_exp_f32_e32 v92, v92
	s_waitcnt lgkmcnt(14)
	v_mfma_f32_32x32x16_bf16 v[16:31], v[128:131], v[152:155], v[16:31]
	ds_read_b64_tr_b16 v[152:153], v252 offset:5120
	ds_read_b64_tr_b16 v[154:155], v252 offset:7168
	v_exp_f32_e32 v93, v93
	v_add_f32_e32 v182, v90, v182
	v_add_f32_e32 v182, v91, v182
	v_cvt_pk_bf16_f32 v133, v90, v91
	s_waitcnt lgkmcnt(13)
	v_mfma_f32_32x32x16_bf16 v[112:127], v[192:195], v[172:175], v[112:127]
	v_exp_f32_e32 v94, v94
	v_exp_f32_e32 v95, v95
	v_add_f32_e32 v182, v92, v182
	v_add_f32_e32 v182, v93, v182
	v_mfma_f32_32x32x16_bf16 v[0:15], v[128:131], v[156:159], v[0:15]
	ds_read_b64_tr_b16 v[156:157], v252 offset:5632
	ds_read_b64_tr_b16 v[158:159], v252 offset:7680
	v_cvt_pk_bf16_f32 v134, v92, v93
	v_cvt_pk_bf16_f32 v135, v94, v95
	v_add_f32_e32 v182, v94, v182
	v_add_f32_e32 v182, v95, v182
	v_exp_f32_e32 v64, v64
	s_waitcnt lgkmcnt(14)
	v_mfma_f32_32x32x16_bf16 v[96:111], v[196:199], v[172:175], v[96:111]
	v_exp_f32_e32 v65, v65
	v_exp_f32_e32 v66, v66
	v_exp_f32_e32 v67, v67
	v_add_f32_e32 v182, v64, v182
	s_waitcnt lgkmcnt(6)
	v_mfma_f32_32x32x16_bf16 v[48:63], v[132:135], v[144:147], v[48:63]
	ds_read_b64_tr_b16 v[144:145], v252 offset:8192
	ds_read_b64_tr_b16 v[146:147], v252 offset:10240
	v_add_f32_e32 v182, v65, v182
	v_cvt_pk_bf16_f32 v136, v64, v65
	v_exp_f32_e32 v68, v68
	v_exp_f32_e32 v69, v69
	v_mfma_f32_32x32x16_bf16 v[112:127], v[200:203], v[168:171], v[112:127]
	v_add_f32_e32 v182, v66, v182
	v_add_f32_e32 v182, v67, v182
	v_cvt_pk_bf16_f32 v137, v66, v67
	v_exp_f32_e32 v70, v70
	s_waitcnt lgkmcnt(6)
	v_mfma_f32_32x32x16_bf16 v[32:47], v[132:135], v[148:151], v[32:47]
	ds_read_b64_tr_b16 v[148:149], v252 offset:8704
	ds_read_b64_tr_b16 v[150:151], v252 offset:10752
	v_exp_f32_e32 v71, v71
	v_add_f32_e32 v182, v68, v182
	v_add_f32_e32 v182, v69, v182
	v_cvt_pk_bf16_f32 v138, v68, v69
	v_cvt_pk_bf16_f32 v139, v70, v71
	v_add_f32_e32 v182, v70, v182
	v_mfma_f32_32x32x16_bf16 v[96:111], v[204:207], v[168:171], v[96:111]
	v_add_f32_e32 v182, v71, v182
	v_exp_f32_e32 v72, v72
	v_exp_f32_e32 v73, v73
	v_exp_f32_e32 v74, v74
	s_waitcnt lgkmcnt(6)
	v_mfma_f32_32x32x16_bf16 v[16:31], v[132:135], v[152:155], v[16:31]
	ds_read_b64_tr_b16 v[152:153], v252 offset:9216
	ds_read_b64_tr_b16 v[154:155], v252 offset:11264
	v_exp_f32_e32 v75, v75
	v_add_f32_e32 v182, v72, v182
	v_add_f32_e32 v182, v73, v182
	v_cvt_pk_bf16_f32 v140, v72, v73
	v_mfma_f32_32x32x16_bf16 v[112:127], v[208:211], v[164:167], v[112:127]
	v_exp_f32_e32 v76, v76
	v_exp_f32_e32 v77, v77
	v_add_f32_e32 v182, v74, v182
	v_add_f32_e32 v182, v75, v182
	s_waitcnt lgkmcnt(6)
	v_mfma_f32_32x32x16_bf16 v[0:15], v[132:135], v[156:159], v[0:15]
	ds_read_b64_tr_b16 v[156:157], v252 offset:9728
	ds_read_b64_tr_b16 v[158:159], v252 offset:11776
	v_cvt_pk_bf16_f32 v141, v74, v75
	v_exp_f32_e32 v78, v78
	v_exp_f32_e32 v79, v79
	v_add_f32_e32 v182, v76, v182
	v_mfma_f32_32x32x16_bf16 v[96:111], v[212:215], v[164:167], v[96:111]
	v_add_f32_e32 v182, v77, v182
	v_cvt_pk_bf16_f32 v142, v76, v77
	v_cvt_pk_bf16_f32 v143, v78, v79
	v_add_f32_e32 v182, v78, v182
	v_add_f32_e32 v182, v79, v182
	s_cmp_lt_i32 s55, 0
	s_cselect_b32 s100, -1.0, 1.0
	v_mul_f32_e32 v185, s100, v186
	v_mfma_f32_32x32x16_bf16 v[112:127], v[216:219], v[160:163], v[112:127]
	v_fma_f32 v187, -v185, v183, s16
	v_fmamk_f32 v80, v185, 0x00000000, v187
	v_fmamk_f32 v81, v185, 0x3f800000, v187
	v_fmamk_f32 v82, v185, 0x40000000, v187
	v_fmamk_f32 v83, v185, 0x40400000, v187
	v_fmamk_f32 v84, v185, 0x41000000, v187
	v_mfma_f32_32x32x16_bf16 v[96:111], v[220:223], v[160:163], v[96:111]
	v_fmamk_f32 v85, v185, 0x41100000, v187
	v_fmamk_f32 v86, v185, 0x41200000, v187
	v_fmamk_f32 v87, v185, 0x41300000, v187
	v_fmamk_f32 v88, v185, 0x41800000, v187
	v_fmamk_f32 v89, v185, 0x41880000, v187
	v_fmamk_f32 v90, v185, 0x41900000, v187
	s_waitcnt lgkmcnt(6)
	v_mfma_f32_32x32x16_bf16 v[48:63], v[136:139], v[144:147], v[48:63]
	ds_read_b64_tr_b16 v[144:145], v252 offset:12288
	ds_read_b64_tr_b16 v[146:147], v252 offset:14336
	v_fmamk_f32 v91, v185, 0x41980000, v187
	v_fmamk_f32 v92, v185, 0x41c00000, v187
	v_fmamk_f32 v93, v185, 0x41c80000, v187
	v_fmamk_f32 v94, v185, 0x41d00000, v187
	v_fmamk_f32 v95, v185, 0x41d80000, v187
	v_fmamk_f32 v64, v185, 0x42000000, v187
	s_waitcnt lgkmcnt(6)
; #define SBAR() __builtin_amdgcn_sched_barrier(0)
; template <int KS> __device__ __forceinline__ void pv_ks(f32x16* o, int vb, bf16x8 pa) {
;     const s16x4 l0 = tr_read<v_rd_off(0, KS, 0)>(vb), h0 = tr_read<v_rd_off(0, KS, 1)>(vb), l1 = tr_read<v_rd_off(1, KS, 0)>(vb), h1 = tr_read<v_rd_off(1, KS, 1)>(vb);
;     const s16x4 l2 = tr_read<v_rd_off(2, KS, 0)>(vb), h2 = tr_read<v_rd_off(2, KS, 1)>(vb), l3 = tr_read<v_rd_off(3, KS, 0)>(vb), h3 = tr_read<v_rd_off(3, KS, 1)>(vb);
;     ...
;     asm volatile("s_waitcnt lgkmcnt(6)" ::: "memory"); SBAR();
;     o[0] = __builtin_amdgcn_mfma_f32_32x32x16_bf16(pa, PK(l0, h0), o[0], 0, 0, 0);
;     asm volatile("s_waitcnt lgkmcnt(4)" ::: "memory"); SBAR();
;     o[1] = __builtin_amdgcn_mfma_f32_32x32x16_bf16(pa, PK(l1, h1), o[1], 0, 0, 0);
;     asm volatile("s_waitcnt lgkmcnt(2)" ::: "memory"); SBAR();
;     o[2] = __builtin_amdgcn_mfma_f32_32x32x16_bf16(pa, PK(l2, h2), o[2], 0, 0, 0);
;     asm volatile("s_waitcnt lgkmcnt(0)" ::: "memory"); SBAR();
;     o[3] = __builtin_amdgcn_mfma_f32_32x32x16_bf16(pa, PK(l3, h3), o[3], 0, 0, 0);
;     ...
; }
; __device__ __forceinline__ void pv_d0(f32x16* o, int vb, bf16x8 pa0, bf16x8 pa1, bf16x8 pa2, bf16x8 pa3) {
;     __builtin_amdgcn_s_setprio(1);
;     pv_ks<0>(o, vb, pa0); pv_ks<1>(o, vb, pa1); pv_ks<2>(o, vb, pa2); pv_ks<3>(o, vb, pa3);
;     __builtin_amdgcn_s_setprio(0);
; }
; __device__ __forceinline__ void exp_half(f32x16& p) {
; #pragma unroll
;     for (int r = 0; r < 16; ++r) p[r] = __builtin_amdgcn_exp2f(p[r]);
; }
; __device__ __forceinline__ void pack_p(const f32x16& p0, const f32x16& p1, float& l_reg, bf16x8& pa0, bf16x8& pa1, bf16x8& pa2, bf16x8& pa3) {
;     float ps = 0;
; #pragma unroll
;     for (int r = 0; r < 16; ++r) ps += p0[r];
; #pragma unroll
;     for (int r = 0; r < 16; ++r) ps += p1[r];
;     l_reg += ps;
;     ...
;     PK4(p0, 0, pa0); PK4(p0, 8, pa1); PK4(p1, 0, pa2); PK4(p1, 8, pa3);
;     ...
; }
; __device__ __forceinline__ void bias_init(f32x16& p0, f32x16& p1, float base, float nslope2, float nM2, int rel  ) {
;     if (rel <= -63 || rel >= 31) {
;         const float sg = (rel < 0) ? -nslope2 : nslope2, lbv = fmaf(-sg, base, nM2);
; #pragma unroll
;         for (int r = 0; r < 16; ++r) { p0[r] = fmaf((float)((r & 3) + 8 * (r >> 2)), sg, lbv); p1[r] = fmaf((float)((r & 3) + 8 * (r >> 2) + 32), sg, lbv); }
;     } else {
; #pragma unroll
	v_mfma_f32_32x32x16_bf16 v[32:47], v[136:139], v[148:151], v[32:47]
	ds_read_b64_tr_b16 v[148:149], v252 offset:12800
	ds_read_b64_tr_b16 v[150:151], v252 offset:14848
	v_fmamk_f32 v65, v185, 0x42040000, v187
	v_fmamk_f32 v66, v185, 0x42080000, v187
	v_fmamk_f32 v67, v185, 0x420c0000, v187
	v_fmamk_f32 v68, v185, 0x42200000, v187
	v_fmamk_f32 v69, v185, 0x42240000, v187
	v_fmamk_f32 v70, v185, 0x42280000, v187
	s_waitcnt lgkmcnt(6)
	v_mfma_f32_32x32x16_bf16 v[16:31], v[136:139], v[152:155], v[16:31]
	ds_read_b64_tr_b16 v[152:153], v252 offset:13312
	ds_read_b64_tr_b16 v[154:155], v252 offset:15360
	v_fmamk_f32 v71, v185, 0x422c0000, v187
	v_fmamk_f32 v72, v185, 0x42400000, v187
	v_fmamk_f32 v73, v185, 0x42440000, v187
	v_fmamk_f32 v74, v185, 0x42480000, v187
	v_fmamk_f32 v75, v185, 0x424c0000, v187
	v_fmamk_f32 v76, v185, 0x42600000, v187
	s_waitcnt lgkmcnt(6)
	v_mfma_f32_32x32x16_bf16 v[0:15], v[136:139], v[156:159], v[0:15]
	ds_read_b64_tr_b16 v[156:157], v252 offset:13824
	ds_read_b64_tr_b16 v[158:159], v252 offset:15872
	v_fmamk_f32 v77, v185, 0x42640000, v187
	v_fmamk_f32 v78, v185, 0x42680000, v187
	v_fmamk_f32 v79, v185, 0x426c0000, v187
	v_exp_f32_e32 v112, v112
	v_exp_f32_e32 v113, v113
	s_waitcnt lgkmcnt(6)
	v_mfma_f32_32x32x16_bf16 v[48:63], v[140:143], v[144:147], v[48:63]
	ds_read_b64_tr_b16 v[144:145], v252 offset:16384
	ds_read_b64_tr_b16 v[146:147], v252 offset:18432
	v_exp_f32_e32 v114, v114
	v_exp_f32_e32 v115, v115
	v_add_f32_e32 v182, v112, v182
	v_add_f32_e32 v182, v113, v182
	s_waitcnt lgkmcnt(6)
	v_mfma_f32_32x32x16_bf16 v[32:47], v[140:143], v[148:151], v[32:47]
	ds_read_b64_tr_b16 v[148:149], v252 offset:16896
	ds_read_b64_tr_b16 v[150:151], v252 offset:18944
	v_cvt_pk_bf16_f32 v128, v112, v113
	v_exp_f32_e32 v116, v116
	v_exp_f32_e32 v117, v117
	v_add_f32_e32 v182, v114, v182
	s_waitcnt lgkmcnt(6)
	v_mfma_f32_32x32x16_bf16 v[16:31], v[140:143], v[152:155], v[16:31]
	ds_read_b64_tr_b16 v[152:153], v252 offset:17408
	ds_read_b64_tr_b16 v[154:155], v252 offset:19456
	v_add_f32_e32 v182, v115, v182
	v_cvt_pk_bf16_f32 v129, v114, v115
	v_exp_f32_e32 v118, v118
	v_exp_f32_e32 v119, v119
	s_waitcnt lgkmcnt(6)
	v_mfma_f32_32x32x16_bf16 v[0:15], v[140:143], v[156:159], v[0:15]
	ds_read_b64_tr_b16 v[156:157], v252 offset:17920
	ds_read_b64_tr_b16 v[158:159], v252 offset:19968
	v_add_f32_e32 v182, v116, v182
	v_add_f32_e32 v182, v117, v182
	v_cvt_pk_bf16_f32 v130, v116, v117
	v_cvt_pk_bf16_f32 v131, v118, v119
	v_add_f32_e32 v182, v118, v182
	v_add_f32_e32 v182, v119, v182
	s_add_i32 s100, s55, 62
	s_cmp_lt_u32 s100, 93
	s_cbranch_scc0 .Lsym_nodiag_s0
	v_add_f32_e32 v190, 0x00000000, v183
	v_add_f32_e32 v191, 0xc2000000, v183
	v_fma_f32 v80, |v190|, v186, s16
	v_fma_f32 v64, |v191|, v186, s16
	v_add_f32_e32 v190, 0xbf800000, v183
	v_add_f32_e32 v191, 0xc2040000, v183
	v_fma_f32 v81, |v190|, v186, s16
	v_fma_f32 v65, |v191|, v186, s16
	v_add_f32_e32 v190, 0xc0000000, v183
	v_add_f32_e32 v191, 0xc2080000, v183
	v_fma_f32 v82, |v190|, v186, s16
	v_fma_f32 v66, |v191|, v186, s16
	v_add_f32_e32 v190, 0xc0400000, v183
	v_add_f32_e32 v191, 0xc20c0000, v183
	v_fma_f32 v83, |v190|, v186, s16
	v_fma_f32 v67, |v191|, v186, s16
	v_add_f32_e32 v190, 0xc1000000, v183
	v_add_f32_e32 v191, 0xc2200000, v183
	v_fma_f32 v84, |v190|, v186, s16
	v_fma_f32 v68, |v191|, v186, s16
	v_add_f32_e32 v190, 0xc1100000, v183
	v_add_f32_e32 v191, 0xc2240000, v183
	v_fma_f32 v85, |v190|, v186, s16
	v_fma_f32 v69, |v191|, v186, s16
	v_add_f32_e32 v190, 0xc1200000, v183
	v_add_f32_e32 v191, 0xc2280000, v183
	v_fma_f32 v86, |v190|, v186, s16
	v_fma_f32 v70, |v191|, v186, s16
	v_add_f32_e32 v190, 0xc1300000, v183
	v_add_f32_e32 v191, 0xc22c0000, v183
	v_fma_f32 v87, |v190|, v186, s16
	v_fma_f32 v71, |v191|, v186, s16
	v_add_f32_e32 v190, 0xc1800000, v183
	v_add_f32_e32 v191, 0xc2400000, v183
	v_fma_f32 v88, |v190|, v186, s16
	v_fma_f32 v72, |v191|, v186, s16
	v_add_f32_e32 v190, 0xc1880000, v183
	v_add_f32_e32 v191, 0xc2440000, v183
	v_fma_f32 v89, |v190|, v186, s16
	v_fma_f32 v73, |v191|, v186, s16
	v_add_f32_e32 v190, 0xc1900000, v183
	v_add_f32_e32 v191, 0xc2480000, v183
	v_fma_f32 v90, |v190|, v186, s16
	v_fma_f32 v74, |v191|, v186, s16
	v_add_f32_e32 v190, 0xc1980000, v183
	v_add_f32_e32 v191, 0xc24c0000, v183
	v_fma_f32 v91, |v190|, v186, s16
	v_fma_f32 v75, |v191|, v186, s16
	v_add_f32_e32 v190, 0xc1c00000, v183
	v_add_f32_e32 v191, 0xc2600000, v183
	v_fma_f32 v92, |v190|, v186, s16
	v_fma_f32 v76, |v191|, v186, s16
	v_add_f32_e32 v190, 0xc1c80000, v183
	v_add_f32_e32 v191, 0xc2640000, v183
	v_fma_f32 v93, |v190|, v186, s16
	v_fma_f32 v77, |v191|, v186, s16
	v_add_f32_e32 v190, 0xc1d00000, v183
	v_add_f32_e32 v191, 0xc2680000, v183
	v_fma_f32 v94, |v190|, v186, s16
	v_fma_f32 v78, |v191|, v186, s16
	v_add_f32_e32 v190, 0xc1d80000, v183
	v_add_f32_e32 v191, 0xc26c0000, v183
	v_fma_f32 v95, |v190|, v186, s16
	v_fma_f32 v79, |v191|, v186, s16

; template <int KS> __device__ __forceinline__ void pv_ks(f32x16* o, int vb, bf16x8 pa) {
;     const s16x4 l0 = tr_read<v_rd_off(0, KS, 0)>(vb), h0 = tr_read<v_rd_off(0, KS, 1)>(vb), l1 = tr_read<v_rd_off(1, KS, 0)>(vb), h1 = tr_read<v_rd_off(1, KS, 1)>(vb);
;     const s16x4 l2 = tr_read<v_rd_off(2, KS, 0)>(vb), h2 = tr_read<v_rd_off(2, KS, 1)>(vb), l3 = tr_read<v_rd_off(3, KS, 0)>(vb), h3 = tr_read<v_rd_off(3, KS, 1)>(vb);
;     ...
;     asm volatile("s_waitcnt lgkmcnt(6)" ::: "memory"); SBAR();
;     o[0] = __builtin_amdgcn_mfma_f32_32x32x16_bf16(pa, PK(l0, h0), o[0], 0, 0, 0);
;     asm volatile("s_waitcnt lgkmcnt(4)" ::: "memory"); SBAR();
;     o[1] = __builtin_amdgcn_mfma_f32_32x32x16_bf16(pa, PK(l1, h1), o[1], 0, 0, 0);
;     asm volatile("s_waitcnt lgkmcnt(2)" ::: "memory"); SBAR();
;     o[2] = __builtin_amdgcn_mfma_f32_32x32x16_bf16(pa, PK(l2, h2), o[2], 0, 0, 0);
;     asm volatile("s_waitcnt lgkmcnt(0)" ::: "memory"); SBAR();
;     o[3] = __builtin_amdgcn_mfma_f32_32x32x16_bf16(pa, PK(l3, h3), o[3], 0, 0, 0);
;     ...
; }
; __device__ __forceinline__ void pv_d0(f32x16* o, int vb, bf16x8 pa0, bf16x8 pa1, bf16x8 pa2, bf16x8 pa3) {
;     __builtin_amdgcn_s_setprio(1);
;     pv_ks<0>(o, vb, pa0); pv_ks<1>(o, vb, pa1); pv_ks<2>(o, vb, pa2); pv_ks<3>(o, vb, pa3);
;     __builtin_amdgcn_s_setprio(0);
; }
; __device__ __forceinline__ void exp_half(f32x16& p) {
; #pragma unroll
;     for (int r = 0; r < 16; ++r) p[r] = __builtin_amdgcn_exp2f(p[r]);
; }
; __device__ __forceinline__ void pack_p(const f32x16& p0, const f32x16& p1, float& l_reg, bf16x8& pa0, bf16x8& pa1, bf16x8& pa2, bf16x8& pa3) {
;     float ps = 0;
; #pragma unroll
;     for (int r = 0; r < 16; ++r) ps += p0[r];
; #pragma unroll
;     for (int r = 0; r < 16; ++r) ps += p1[r];
;     l_reg += ps;
;     ...
;     PK4(p0, 0, pa0); PK4(p0, 8, pa1); PK4(p1, 0, pa2); PK4(p1, 8, pa3);
;     ...
; }
; template <int ND0> __device__ __forceinline__ void qkt(f32x16& p0, f32x16& p1, const char* Ks, const bf16x8* qr, int r32, int hi, int colB0) {
; #pragma unroll
;     for (int d0 = 0; d0 < ND0; ++d0) { const int cb = colB0 + (d0 * 16 + hi * 8) * 2;
;         const bf16x8 b0 = *reinterpret_cast<const bf16x8*>(Ks + KSWZ(r32, cb));
;         const bf16x8 b1 = *reinterpret_cast<const bf16x8*>(Ks + KSWZ(32 + r32, cb));
;         p0 = __builtin_amdgcn_mfma_f32_32x32x16_bf16(b0, qr[d0], p0, 0, 0, 0);
.Lsym_nostage_s1:
	s_waitcnt lgkmcnt(14)
	v_mfma_f32_32x32x16_bf16 v[48:63], v[128:131], v[144:147], v[48:63]
	ds_read_b64_tr_b16 v[144:145], v252 offset:20480
	ds_read_b64_tr_b16 v[146:147], v252 offset:22528
	v_exp_f32_e32 v120, v120
	v_exp_f32_e32 v121, v121
	v_exp_f32_e32 v122, v122
	s_waitcnt lgkmcnt(14)
	v_mfma_f32_32x32x16_bf16 v[32:47], v[128:131], v[148:151], v[32:47]
	ds_read_b64_tr_b16 v[148:149], v252 offset:20992
	ds_read_b64_tr_b16 v[150:151], v252 offset:23040
	v_exp_f32_e32 v123, v123
	v_add_f32_e32 v182, v120, v182
	v_add_f32_e32 v182, v121, v182
	v_cvt_pk_bf16_f32 v132, v120, v121
	v_exp_f32_e32 v124, v124
	s_waitcnt lgkmcnt(14)
	v_mfma_f32_32x32x16_bf16 v[16:31], v[128:131], v[152:155], v[16:31]
	ds_read_b64_tr_b16 v[152:153], v252 offset:21504
	ds_read_b64_tr_b16 v[154:155], v252 offset:23552
	v_exp_f32_e32 v125, v125
	v_add_f32_e32 v182, v122, v182
	v_add_f32_e32 v182, v123, v182
	v_cvt_pk_bf16_f32 v133, v122, v123
	s_waitcnt lgkmcnt(13)
	v_mfma_f32_32x32x16_bf16 v[80:95], v[192:195], v[172:175], v[80:95]
	v_exp_f32_e32 v126, v126
	v_exp_f32_e32 v127, v127
	v_add_f32_e32 v182, v124, v182
	v_add_f32_e32 v182, v125, v182
	v_mfma_f32_32x32x16_bf16 v[0:15], v[128:131], v[156:159], v[0:15]
	ds_read_b64_tr_b16 v[156:157], v252 offset:22016
	ds_read_b64_tr_b16 v[158:159], v252 offset:24064
	v_cvt_pk_bf16_f32 v134, v124, v125
	v_cvt_pk_bf16_f32 v135, v126, v127
	v_add_f32_e32 v182, v126, v182
	v_add_f32_e32 v182, v127, v182
	v_exp_f32_e32 v96, v96
	s_waitcnt lgkmcnt(14)
	v_mfma_f32_32x32x16_bf16 v[64:79], v[196:199], v[172:175], v[64:79]
	v_exp_f32_e32 v97, v97
	v_exp_f32_e32 v98, v98
	v_exp_f32_e32 v99, v99
	v_add_f32_e32 v182, v96, v182
	s_waitcnt lgkmcnt(6)
	v_mfma_f32_32x32x16_bf16 v[48:63], v[132:135], v[144:147], v[48:63]
	ds_read_b64_tr_b16 v[144:145], v252 offset:24576
	ds_read_b64_tr_b16 v[146:147], v252 offset:26624
	v_add_f32_e32 v182, v97, v182
	v_cvt_pk_bf16_f32 v136, v96, v97
	v_exp_f32_e32 v100, v100
	v_exp_f32_e32 v101, v101
	v_mfma_f32_32x32x16_bf16 v[80:95], v[200:203], v[168:171], v[80:95]
	v_add_f32_e32 v182, v98, v182
	v_add_f32_e32 v182, v99, v182
	v_cvt_pk_bf16_f32 v137, v98, v99
	v_exp_f32_e32 v102, v102
	s_waitcnt lgkmcnt(6)
	v_mfma_f32_32x32x16_bf16 v[32:47], v[132:135], v[148:151], v[32:47]
	ds_read_b64_tr_b16 v[148:149], v252 offset:25088
	ds_read_b64_tr_b16 v[150:151], v252 offset:27136
	v_exp_f32_e32 v103, v103
	v_add_f32_e32 v182, v100, v182
	v_add_f32_e32 v182, v101, v182
	v_cvt_pk_bf16_f32 v138, v100, v101
	v_cvt_pk_bf16_f32 v139, v102, v103
	v_add_f32_e32 v182, v102, v182
	v_mfma_f32_32x32x16_bf16 v[64:79], v[204:207], v[168:171], v[64:79]
	v_add_f32_e32 v182, v103, v182
	v_exp_f32_e32 v104, v104
	v_exp_f32_e32 v105, v105
	v_exp_f32_e32 v106, v106
	s_waitcnt lgkmcnt(6)
	v_mfma_f32_32x32x16_bf16 v[16:31], v[132:135], v[152:155], v[16:31]
	ds_read_b64_tr_b16 v[152:153], v252 offset:25600
	ds_read_b64_tr_b16 v[154:155], v252 offset:27648
	v_exp_f32_e32 v107, v107
	v_add_f32_e32 v182, v104, v182
	v_add_f32_e32 v182, v105, v182
	v_cvt_pk_bf16_f32 v140, v104, v105
	v_mfma_f32_32x32x16_bf16 v[80:95], v[208:211], v[164:167], v[80:95]
	v_exp_f32_e32 v108, v108
	v_exp_f32_e32 v109, v109
	v_add_f32_e32 v182, v106, v182
	v_add_f32_e32 v182, v107, v182
	s_waitcnt lgkmcnt(6)
	v_mfma_f32_32x32x16_bf16 v[0:15], v[132:135], v[156:159], v[0:15]
	ds_read_b64_tr_b16 v[156:157], v252 offset:26112
	ds_read_b64_tr_b16 v[158:159], v252 offset:28160
	v_cvt_pk_bf16_f32 v141, v106, v107
	v_exp_f32_e32 v110, v110
	v_exp_f32_e32 v111, v111
	v_add_f32_e32 v182, v108, v182
	v_mfma_f32_32x32x16_bf16 v[64:79], v[212:215], v[164:167], v[64:79]
	v_add_f32_e32 v182, v109, v182
	v_cvt_pk_bf16_f32 v142, v108, v109
	v_cvt_pk_bf16_f32 v143, v110, v111
	v_add_f32_e32 v182, v110, v182
	v_add_f32_e32 v182, v111, v182
	s_cmp_lt_i32 s55, 0
	s_cselect_b32 s100, -1.0, 1.0
	v_mul_f32_e32 v185, s100, v186
	v_mfma_f32_32x32x16_bf16 v[80:95], v[216:219], v[160:163], v[80:95]
	v_fma_f32 v187, -v185, v183, s16
	v_fmamk_f32 v112, v185, 0x00000000, v187
	v_fmamk_f32 v113, v185, 0x3f800000, v187
	v_fmamk_f32 v114, v185, 0x40000000, v187
	v_fmamk_f32 v115, v185, 0x40400000, v187
	v_fmamk_f32 v116, v185, 0x41000000, v187
	v_mfma_f32_32x32x16_bf16 v[64:79], v[220:223], v[160:163], v[64:79]
	v_fmamk_f32 v117, v185, 0x41100000, v187
	v_fmamk_f32 v118, v185, 0x41200000, v187
	v_fmamk_f32 v119, v185, 0x41300000, v187
	v_fmamk_f32 v120, v185, 0x41800000, v187
	v_fmamk_f32 v121, v185, 0x41880000, v187
	v_fmamk_f32 v122, v185, 0x41900000, v187
	s_waitcnt lgkmcnt(6)
	v_mfma_f32_32x32x16_bf16 v[48:63], v[136:139], v[144:147], v[48:63]
	ds_read_b64_tr_b16 v[144:145], v252 offset:28672
	ds_read_b64_tr_b16 v[146:147], v252 offset:30720
	v_fmamk_f32 v123, v185, 0x41980000, v187
	v_fmamk_f32 v124, v185, 0x41c00000, v187
	v_fmamk_f32 v125, v185, 0x41c80000, v187
	v_fmamk_f32 v126, v185, 0x41d00000, v187
	v_fmamk_f32 v127, v185, 0x41d80000, v187
	v_fmamk_f32 v96, v185, 0x42000000, v187
	s_waitcnt lgkmcnt(6)
; #define SBAR() __builtin_amdgcn_sched_barrier(0)
; template <int KS> __device__ __forceinline__ void pv_ks(f32x16* o, int vb, bf16x8 pa) {
;     const s16x4 l0 = tr_read<v_rd_off(0, KS, 0)>(vb), h0 = tr_read<v_rd_off(0, KS, 1)>(vb), l1 = tr_read<v_rd_off(1, KS, 0)>(vb), h1 = tr_read<v_rd_off(1, KS, 1)>(vb);
;     const s16x4 l2 = tr_read<v_rd_off(2, KS, 0)>(vb), h2 = tr_read<v_rd_off(2, KS, 1)>(vb), l3 = tr_read<v_rd_off(3, KS, 0)>(vb), h3 = tr_read<v_rd_off(3, KS, 1)>(vb);
;     ...
;     asm volatile("s_waitcnt lgkmcnt(6)" ::: "memory"); SBAR();
;     o[0] = __builtin_amdgcn_mfma_f32_32x32x16_bf16(pa, PK(l0, h0), o[0], 0, 0, 0);
;     asm volatile("s_waitcnt lgkmcnt(4)" ::: "memory"); SBAR();
;     o[1] = __builtin_amdgcn_mfma_f32_32x32x16_bf16(pa, PK(l1, h1), o[1], 0, 0, 0);
;     asm volatile("s_waitcnt lgkmcnt(2)" ::: "memory"); SBAR();
;     o[2] = __builtin_amdgcn_mfma_f32_32x32x16_bf16(pa, PK(l2, h2), o[2], 0, 0, 0);
;     asm volatile("s_waitcnt lgkmcnt(0)" ::: "memory"); SBAR();
;     o[3] = __builtin_amdgcn_mfma_f32_32x32x16_bf16(pa, PK(l3, h3), o[3], 0, 0, 0);
;     ...
; }
; __device__ __forceinline__ void pv_d0(f32x16* o, int vb, bf16x8 pa0, bf16x8 pa1, bf16x8 pa2, bf16x8 pa3) {
;     __builtin_amdgcn_s_setprio(1);
;     pv_ks<0>(o, vb, pa0); pv_ks<1>(o, vb, pa1); pv_ks<2>(o, vb, pa2); pv_ks<3>(o, vb, pa3);
;     __builtin_amdgcn_s_setprio(0);
; }
; __device__ __forceinline__ void exp_half(f32x16& p) {
; #pragma unroll
;     for (int r = 0; r < 16; ++r) p[r] = __builtin_amdgcn_exp2f(p[r]);
; }
; __device__ __forceinline__ void pack_p(const f32x16& p0, const f32x16& p1, float& l_reg, bf16x8& pa0, bf16x8& pa1, bf16x8& pa2, bf16x8& pa3) {
;     float ps = 0;
; #pragma unroll
;     for (int r = 0; r < 16; ++r) ps += p0[r];
; #pragma unroll
;     for (int r = 0; r < 16; ++r) ps += p1[r];
;     l_reg += ps;
;     ...
;     PK4(p0, 0, pa0); PK4(p0, 8, pa1); PK4(p1, 0, pa2); PK4(p1, 8, pa3);
;     ...
; }
; __device__ __forceinline__ void bias_init(f32x16& p0, f32x16& p1, float base, float nslope2, float nM2, int rel  ) {
;     if (rel <= -63 || rel >= 31) {
;         const float sg = (rel < 0) ? -nslope2 : nslope2, lbv = fmaf(-sg, base, nM2);
; #pragma unroll
;         for (int r = 0; r < 16; ++r) { p0[r] = fmaf((float)((r & 3) + 8 * (r >> 2)), sg, lbv); p1[r] = fmaf((float)((r & 3) + 8 * (r >> 2) + 32), sg, lbv); }
;     } else {
; #pragma unroll
	v_mfma_f32_32x32x16_bf16 v[32:47], v[136:139], v[148:151], v[32:47]
	ds_read_b64_tr_b16 v[148:149], v252 offset:29184
	ds_read_b64_tr_b16 v[150:151], v252 offset:31232
	v_fmamk_f32 v97, v185, 0x42040000, v187
	v_fmamk_f32 v98, v185, 0x42080000, v187
	v_fmamk_f32 v99, v185, 0x420c0000, v187
	v_fmamk_f32 v100, v185, 0x42200000, v187
	v_fmamk_f32 v101, v185, 0x42240000, v187
	v_fmamk_f32 v102, v185, 0x42280000, v187
	s_waitcnt lgkmcnt(6)
	v_mfma_f32_32x32x16_bf16 v[16:31], v[136:139], v[152:155], v[16:31]
	ds_read_b64_tr_b16 v[152:153], v252 offset:29696
	ds_read_b64_tr_b16 v[154:155], v252 offset:31744
	v_fmamk_f32 v103, v185, 0x422c0000, v187
	v_fmamk_f32 v104, v185, 0x42400000, v187
	v_fmamk_f32 v105, v185, 0x42440000, v187
	v_fmamk_f32 v106, v185, 0x42480000, v187
	v_fmamk_f32 v107, v185, 0x424c0000, v187
	v_fmamk_f32 v108, v185, 0x42600000, v187
	s_waitcnt lgkmcnt(6)
	v_mfma_f32_32x32x16_bf16 v[0:15], v[136:139], v[156:159], v[0:15]
	ds_read_b64_tr_b16 v[156:157], v252 offset:30208
	ds_read_b64_tr_b16 v[158:159], v252 offset:32256
	v_fmamk_f32 v109, v185, 0x42640000, v187
	v_fmamk_f32 v110, v185, 0x42680000, v187
	v_fmamk_f32 v111, v185, 0x426c0000, v187
	v_exp_f32_e32 v80, v80
	v_exp_f32_e32 v81, v81
	s_waitcnt lgkmcnt(6)
	v_mfma_f32_32x32x16_bf16 v[48:63], v[140:143], v[144:147], v[48:63]
	ds_read_b64_tr_b16 v[144:145], v252 offset:32768
	ds_read_b64_tr_b16 v[146:147], v252 offset:34816
	v_exp_f32_e32 v82, v82
	v_exp_f32_e32 v83, v83
	v_add_f32_e32 v182, v80, v182
	v_add_f32_e32 v182, v81, v182
	s_waitcnt lgkmcnt(6)
	v_mfma_f32_32x32x16_bf16 v[32:47], v[140:143], v[148:151], v[32:47]
	ds_read_b64_tr_b16 v[148:149], v252 offset:33280
	ds_read_b64_tr_b16 v[150:151], v252 offset:35328
	v_cvt_pk_bf16_f32 v128, v80, v81
	v_exp_f32_e32 v84, v84
	v_exp_f32_e32 v85, v85
	v_add_f32_e32 v182, v82, v182
	s_waitcnt lgkmcnt(6)
	v_mfma_f32_32x32x16_bf16 v[16:31], v[140:143], v[152:155], v[16:31]
	ds_read_b64_tr_b16 v[152:153], v252 offset:33792
	ds_read_b64_tr_b16 v[154:155], v252 offset:35840
	v_add_f32_e32 v182, v83, v182
	v_cvt_pk_bf16_f32 v129, v82, v83
	v_exp_f32_e32 v86, v86
	v_exp_f32_e32 v87, v87
	s_waitcnt lgkmcnt(6)
	v_mfma_f32_32x32x16_bf16 v[0:15], v[140:143], v[156:159], v[0:15]
	ds_read_b64_tr_b16 v[156:157], v252 offset:34304
	ds_read_b64_tr_b16 v[158:159], v252 offset:36352
	v_add_f32_e32 v182, v84, v182
	v_add_f32_e32 v182, v85, v182
	v_cvt_pk_bf16_f32 v130, v84, v85
	v_cvt_pk_bf16_f32 v131, v86, v87
	v_add_f32_e32 v182, v86, v182
	v_add_f32_e32 v182, v87, v182
	s_add_i32 s100, s55, 62
	s_cmp_lt_u32 s100, 93
	s_cbranch_scc0 .Lsym_nodiag_s1
	v_add_f32_e32 v190, 0x00000000, v183
	v_add_f32_e32 v191, 0xc2000000, v183
	v_fma_f32 v112, |v190|, v186, s16
	v_fma_f32 v96, |v191|, v186, s16
	v_add_f32_e32 v190, 0xbf800000, v183
	v_add_f32_e32 v191, 0xc2040000, v183
	v_fma_f32 v113, |v190|, v186, s16
	v_fma_f32 v97, |v191|, v186, s16
	v_add_f32_e32 v190, 0xc0000000, v183
	v_add_f32_e32 v191, 0xc2080000, v183
	v_fma_f32 v114, |v190|, v186, s16
	v_fma_f32 v98, |v191|, v186, s16
	v_add_f32_e32 v190, 0xc0400000, v183
	v_add_f32_e32 v191, 0xc20c0000, v183
	v_fma_f32 v115, |v190|, v186, s16
	v_fma_f32 v99, |v191|, v186, s16
	v_add_f32_e32 v190, 0xc1000000, v183
	v_add_f32_e32 v191, 0xc2200000, v183
	v_fma_f32 v116, |v190|, v186, s16
	v_fma_f32 v100, |v191|, v186, s16
	v_add_f32_e32 v190, 0xc1100000, v183
	v_add_f32_e32 v191, 0xc2240000, v183
	v_fma_f32 v117, |v190|, v186, s16
	v_fma_f32 v101, |v191|, v186, s16
	v_add_f32_e32 v190, 0xc1200000, v183
	v_add_f32_e32 v191, 0xc2280000, v183
	v_fma_f32 v118, |v190|, v186, s16
	v_fma_f32 v102, |v191|, v186, s16
	v_add_f32_e32 v190, 0xc1300000, v183
	v_add_f32_e32 v191, 0xc22c0000, v183
	v_fma_f32 v119, |v190|, v186, s16
	v_fma_f32 v103, |v191|, v186, s16
	v_add_f32_e32 v190, 0xc1800000, v183
	v_add_f32_e32 v191, 0xc2400000, v183
	v_fma_f32 v120, |v190|, v186, s16
	v_fma_f32 v104, |v191|, v186, s16
	v_add_f32_e32 v190, 0xc1880000, v183
	v_add_f32_e32 v191, 0xc2440000, v183
	v_fma_f32 v121, |v190|, v186, s16
	v_fma_f32 v105, |v191|, v186, s16
	v_add_f32_e32 v190, 0xc1900000, v183
	v_add_f32_e32 v191, 0xc2480000, v183
	v_fma_f32 v122, |v190|, v186, s16
	v_fma_f32 v106, |v191|, v186, s16
	v_add_f32_e32 v190, 0xc1980000, v183
	v_add_f32_e32 v191, 0xc24c0000, v183
	v_fma_f32 v123, |v190|, v186, s16
	v_fma_f32 v107, |v191|, v186, s16
	v_add_f32_e32 v190, 0xc1c00000, v183
	v_add_f32_e32 v191, 0xc2600000, v183
	v_fma_f32 v124, |v190|, v186, s16
	v_fma_f32 v108, |v191|, v186, s16
	v_add_f32_e32 v190, 0xc1c80000, v183
	v_add_f32_e32 v191, 0xc2640000, v183
	v_fma_f32 v125, |v190|, v186, s16
	v_fma_f32 v109, |v191|, v186, s16
	v_add_f32_e32 v190, 0xc1d00000, v183
	v_add_f32_e32 v191, 0xc2680000, v183
	v_fma_f32 v126, |v190|, v186, s16
	v_fma_f32 v110, |v191|, v186, s16
	v_add_f32_e32 v190, 0xc1d80000, v183
	v_add_f32_e32 v191, 0xc26c0000, v183
	v_fma_f32 v127, |v190|, v186, s16
	v_fma_f32 v111, |v191|, v186, s16

; template <int KS> __device__ __forceinline__ void pv_ks(f32x16* o, int vb, bf16x8 pa) {
;     const s16x4 l0 = tr_read<v_rd_off(0, KS, 0)>(vb), h0 = tr_read<v_rd_off(0, KS, 1)>(vb), l1 = tr_read<v_rd_off(1, KS, 0)>(vb), h1 = tr_read<v_rd_off(1, KS, 1)>(vb);
;     const s16x4 l2 = tr_read<v_rd_off(2, KS, 0)>(vb), h2 = tr_read<v_rd_off(2, KS, 1)>(vb), l3 = tr_read<v_rd_off(3, KS, 0)>(vb), h3 = tr_read<v_rd_off(3, KS, 1)>(vb);
;     ...
;     asm volatile("s_waitcnt lgkmcnt(6)" ::: "memory"); SBAR();
;     o[0] = __builtin_amdgcn_mfma_f32_32x32x16_bf16(pa, PK(l0, h0), o[0], 0, 0, 0);
;     asm volatile("s_waitcnt lgkmcnt(4)" ::: "memory"); SBAR();
;     o[1] = __builtin_amdgcn_mfma_f32_32x32x16_bf16(pa, PK(l1, h1), o[1], 0, 0, 0);
;     asm volatile("s_waitcnt lgkmcnt(2)" ::: "memory"); SBAR();
;     o[2] = __builtin_amdgcn_mfma_f32_32x32x16_bf16(pa, PK(l2, h2), o[2], 0, 0, 0);
;     asm volatile("s_waitcnt lgkmcnt(0)" ::: "memory"); SBAR();
;     o[3] = __builtin_amdgcn_mfma_f32_32x32x16_bf16(pa, PK(l3, h3), o[3], 0, 0, 0);
;     ...
; }
; __device__ __forceinline__ void pv_d0(f32x16* o, int vb, bf16x8 pa0, bf16x8 pa1, bf16x8 pa2, bf16x8 pa3) {
;     __builtin_amdgcn_s_setprio(1);
;     pv_ks<0>(o, vb, pa0); pv_ks<1>(o, vb, pa1); pv_ks<2>(o, vb, pa2); pv_ks<3>(o, vb, pa3);
;     __builtin_amdgcn_s_setprio(0);
; }
; __device__ __forceinline__ void exp_half(f32x16& p) {
; #pragma unroll
;     for (int r = 0; r < 16; ++r) p[r] = __builtin_amdgcn_exp2f(p[r]);
; }
; __device__ __forceinline__ void pack_p(const f32x16& p0, const f32x16& p1, float& l_reg, bf16x8& pa0, bf16x8& pa1, bf16x8& pa2, bf16x8& pa3) {
;     float ps = 0;
; #pragma unroll
;     for (int r = 0; r < 16; ++r) ps += p0[r];
; #pragma unroll
;     for (int r = 0; r < 16; ++r) ps += p1[r];
;     l_reg += ps;
;     ...
;     PK4(p0, 0, pa0); PK4(p0, 8, pa1); PK4(p1, 0, pa2); PK4(p1, 8, pa3);
;     ...
; }
; template <int ND0> __device__ __forceinline__ void qkt(f32x16& p0, f32x16& p1, const char* Ks, const bf16x8* qr, int r32, int hi, int colB0) {
; #pragma unroll
;     for (int d0 = 0; d0 < ND0; ++d0) { const int cb = colB0 + (d0 * 16 + hi * 8) * 2;
;         const bf16x8 b0 = *reinterpret_cast<const bf16x8*>(Ks + KSWZ(r32, cb));
;         const bf16x8 b1 = *reinterpret_cast<const bf16x8*>(Ks + KSWZ(32 + r32, cb));
;         p0 = __builtin_amdgcn_mfma_f32_32x32x16_bf16(b0, qr[d0], p0, 0, 0, 0);
.Lsym_nostage_s2:
	s_waitcnt lgkmcnt(14)
	v_mfma_f32_32x32x16_bf16 v[48:63], v[128:131], v[144:147], v[48:63]
	ds_read_b64_tr_b16 v[144:145], v252 offset:36864
	ds_read_b64_tr_b16 v[146:147], v252 offset:38912
	v_exp_f32_e32 v88, v88
	v_exp_f32_e32 v89, v89
	v_exp_f32_e32 v90, v90
	s_waitcnt lgkmcnt(14)
	v_mfma_f32_32x32x16_bf16 v[32:47], v[128:131], v[148:151], v[32:47]
	ds_read_b64_tr_b16 v[148:149], v252 offset:37376
	ds_read_b64_tr_b16 v[150:151], v252 offset:39424
	v_exp_f32_e32 v91, v91
	v_add_f32_e32 v182, v88, v182
	v_add_f32_e32 v182, v89, v182
	v_cvt_pk_bf16_f32 v132, v88, v89
	v_exp_f32_e32 v92, v92
	s_waitcnt lgkmcnt(14)
	v_mfma_f32_32x32x16_bf16 v[16:31], v[128:131], v[152:155], v[16:31]
	ds_read_b64_tr_b16 v[152:153], v252 offset:37888
	ds_read_b64_tr_b16 v[154:155], v252 offset:39936
	v_exp_f32_e32 v93, v93
	v_add_f32_e32 v182, v90, v182
	v_add_f32_e32 v182, v91, v182
	v_cvt_pk_bf16_f32 v133, v90, v91
	s_waitcnt lgkmcnt(13)
	v_mfma_f32_32x32x16_bf16 v[112:127], v[192:195], v[172:175], v[112:127]
	v_exp_f32_e32 v94, v94
	v_exp_f32_e32 v95, v95
	v_add_f32_e32 v182, v92, v182
	v_add_f32_e32 v182, v93, v182
	v_mfma_f32_32x32x16_bf16 v[0:15], v[128:131], v[156:159], v[0:15]
	ds_read_b64_tr_b16 v[156:157], v252 offset:38400
	ds_read_b64_tr_b16 v[158:159], v252 offset:40448
	v_cvt_pk_bf16_f32 v134, v92, v93
	v_cvt_pk_bf16_f32 v135, v94, v95
	v_add_f32_e32 v182, v94, v182
	v_add_f32_e32 v182, v95, v182
	v_exp_f32_e32 v64, v64
	s_waitcnt lgkmcnt(14)
	v_mfma_f32_32x32x16_bf16 v[96:111], v[196:199], v[172:175], v[96:111]
	v_exp_f32_e32 v65, v65
	v_exp_f32_e32 v66, v66
	v_exp_f32_e32 v67, v67
	v_add_f32_e32 v182, v64, v182
	s_waitcnt lgkmcnt(6)
	v_mfma_f32_32x32x16_bf16 v[48:63], v[132:135], v[144:147], v[48:63]
	ds_read_b64_tr_b16 v[144:145], v252 offset:40960
	ds_read_b64_tr_b16 v[146:147], v252 offset:43008
	v_add_f32_e32 v182, v65, v182
	v_cvt_pk_bf16_f32 v136, v64, v65
	v_exp_f32_e32 v68, v68
	v_exp_f32_e32 v69, v69
	v_mfma_f32_32x32x16_bf16 v[112:127], v[200:203], v[168:171], v[112:127]
	v_add_f32_e32 v182, v66, v182
	v_add_f32_e32 v182, v67, v182
	v_cvt_pk_bf16_f32 v137, v66, v67
	v_exp_f32_e32 v70, v70
	s_waitcnt lgkmcnt(6)
	v_mfma_f32_32x32x16_bf16 v[32:47], v[132:135], v[148:151], v[32:47]
	ds_read_b64_tr_b16 v[148:149], v252 offset:41472
	ds_read_b64_tr_b16 v[150:151], v252 offset:43520
	v_exp_f32_e32 v71, v71
	v_add_f32_e32 v182, v68, v182
	v_add_f32_e32 v182, v69, v182
	v_cvt_pk_bf16_f32 v138, v68, v69
	v_cvt_pk_bf16_f32 v139, v70, v71
	v_add_f32_e32 v182, v70, v182
	v_mfma_f32_32x32x16_bf16 v[96:111], v[204:207], v[168:171], v[96:111]
	v_add_f32_e32 v182, v71, v182
	v_exp_f32_e32 v72, v72
	v_exp_f32_e32 v73, v73
	v_exp_f32_e32 v74, v74
	s_waitcnt lgkmcnt(6)
	v_mfma_f32_32x32x16_bf16 v[16:31], v[132:135], v[152:155], v[16:31]
	ds_read_b64_tr_b16 v[152:153], v252 offset:41984
	ds_read_b64_tr_b16 v[154:155], v252 offset:44032
	v_exp_f32_e32 v75, v75
	v_add_f32_e32 v182, v72, v182
	v_add_f32_e32 v182, v73, v182
	v_cvt_pk_bf16_f32 v140, v72, v73
	v_mfma_f32_32x32x16_bf16 v[112:127], v[208:211], v[164:167], v[112:127]
	v_exp_f32_e32 v76, v76
	v_exp_f32_e32 v77, v77
	v_add_f32_e32 v182, v74, v182
	v_add_f32_e32 v182, v75, v182
	s_waitcnt lgkmcnt(6)
	v_mfma_f32_32x32x16_bf16 v[0:15], v[132:135], v[156:159], v[0:15]
	ds_read_b64_tr_b16 v[156:157], v252 offset:42496
	ds_read_b64_tr_b16 v[158:159], v252 offset:44544
	v_cvt_pk_bf16_f32 v141, v74, v75
	v_exp_f32_e32 v78, v78
	v_exp_f32_e32 v79, v79
	v_add_f32_e32 v182, v76, v182
	v_mfma_f32_32x32x16_bf16 v[96:111], v[212:215], v[164:167], v[96:111]
	v_add_f32_e32 v182, v77, v182
	v_cvt_pk_bf16_f32 v142, v76, v77
	v_cvt_pk_bf16_f32 v143, v78, v79
	v_add_f32_e32 v182, v78, v182
	v_add_f32_e32 v182, v79, v182
	s_cmp_lt_i32 s55, 0
	s_cselect_b32 s100, -1.0, 1.0
	v_mul_f32_e32 v185, s100, v186
	v_mfma_f32_32x32x16_bf16 v[112:127], v[216:219], v[160:163], v[112:127]
	v_fma_f32 v187, -v185, v183, s16
	v_fmamk_f32 v80, v185, 0x00000000, v187
	v_fmamk_f32 v81, v185, 0x3f800000, v187
	v_fmamk_f32 v82, v185, 0x40000000, v187
	v_fmamk_f32 v83, v185, 0x40400000, v187
	v_fmamk_f32 v84, v185, 0x41000000, v187
	v_mfma_f32_32x32x16_bf16 v[96:111], v[220:223], v[160:163], v[96:111]
	v_fmamk_f32 v85, v185, 0x41100000, v187
	v_fmamk_f32 v86, v185, 0x41200000, v187
	v_fmamk_f32 v87, v185, 0x41300000, v187
	v_fmamk_f32 v88, v185, 0x41800000, v187
	v_fmamk_f32 v89, v185, 0x41880000, v187
	v_fmamk_f32 v90, v185, 0x41900000, v187
	s_waitcnt lgkmcnt(6)
	v_mfma_f32_32x32x16_bf16 v[48:63], v[136:139], v[144:147], v[48:63]
	ds_read_b64_tr_b16 v[144:145], v252 offset:45056
	ds_read_b64_tr_b16 v[146:147], v252 offset:47104
	v_fmamk_f32 v91, v185, 0x41980000, v187
	v_fmamk_f32 v92, v185, 0x41c00000, v187
	v_fmamk_f32 v93, v185, 0x41c80000, v187
	v_fmamk_f32 v94, v185, 0x41d00000, v187
	v_fmamk_f32 v95, v185, 0x41d80000, v187
	v_fmamk_f32 v64, v185, 0x42000000, v187
	s_waitcnt lgkmcnt(6)
; template <int KS> __device__ __forceinline__ void pv_ks(f32x16* o, int vb, bf16x8 pa) {
;     const s16x4 l0 = tr_read<v_rd_off(0, KS, 0)>(vb), h0 = tr_read<v_rd_off(0, KS, 1)>(vb), l1 = tr_read<v_rd_off(1, KS, 0)>(vb), h1 = tr_read<v_rd_off(1, KS, 1)>(vb);
;     const s16x4 l2 = tr_read<v_rd_off(2, KS, 0)>(vb), h2 = tr_read<v_rd_off(2, KS, 1)>(vb), l3 = tr_read<v_rd_off(3, KS, 0)>(vb), h3 = tr_read<v_rd_off(3, KS, 1)>(vb);
;     ...
;     asm volatile("s_waitcnt lgkmcnt(6)" ::: "memory"); SBAR();
;     o[0] = __builtin_amdgcn_mfma_f32_32x32x16_bf16(pa, PK(l0, h0), o[0], 0, 0, 0);
;     asm volatile("s_waitcnt lgkmcnt(4)" ::: "memory"); SBAR();
;     o[1] = __builtin_amdgcn_mfma_f32_32x32x16_bf16(pa, PK(l1, h1), o[1], 0, 0, 0);
;     asm volatile("s_waitcnt lgkmcnt(2)" ::: "memory"); SBAR();
;     o[2] = __builtin_amdgcn_mfma_f32_32x32x16_bf16(pa, PK(l2, h2), o[2], 0, 0, 0);
;     asm volatile("s_waitcnt lgkmcnt(0)" ::: "memory"); SBAR();
;     o[3] = __builtin_amdgcn_mfma_f32_32x32x16_bf16(pa, PK(l3, h3), o[3], 0, 0, 0);
;     ...
; }
; __device__ __forceinline__ void pv_d0(f32x16* o, int vb, bf16x8 pa0, bf16x8 pa1, bf16x8 pa2, bf16x8 pa3) {
;     __builtin_amdgcn_s_setprio(1);
;     pv_ks<0>(o, vb, pa0); pv_ks<1>(o, vb, pa1); pv_ks<2>(o, vb, pa2); pv_ks<3>(o, vb, pa3);
;     __builtin_amdgcn_s_setprio(0);
; }
; __device__ __forceinline__ void exp_half(f32x16& p) {
; #pragma unroll
;     for (int r = 0; r < 16; ++r) p[r] = __builtin_amdgcn_exp2f(p[r]);
; }
; __device__ __forceinline__ void pack_p(const f32x16& p0, const f32x16& p1, float& l_reg, bf16x8& pa0, bf16x8& pa1, bf16x8& pa2, bf16x8& pa3) {
;     float ps = 0;
; #pragma unroll
;     for (int r = 0; r < 16; ++r) ps += p0[r];
; #pragma unroll
;     for (int r = 0; r < 16; ++r) ps += p1[r];
;     l_reg += ps;
;     ...
;     PK4(p0, 0, pa0); PK4(p0, 8, pa1); PK4(p1, 0, pa2); PK4(p1, 8, pa3);
;     ...
; }
; template <int ND0> __device__ __forceinline__ void qkt(f32x16& p0, f32x16& p1, const char* Ks, const bf16x8* qr, int r32, int hi, int colB0) {
; #pragma unroll
;     for (int d0 = 0; d0 < ND0; ++d0) { const int cb = colB0 + (d0 * 16 + hi * 8) * 2;
;         const bf16x8 b0 = *reinterpret_cast<const bf16x8*>(Ks + KSWZ(r32, cb));
;         const bf16x8 b1 = *reinterpret_cast<const bf16x8*>(Ks + KSWZ(32 + r32, cb));
;         p0 = __builtin_amdgcn_mfma_f32_32x32x16_bf16(b0, qr[d0], p0, 0, 0, 0);
	v_mfma_f32_32x32x16_bf16 v[32:47], v[136:139], v[148:151], v[32:47]
	ds_read_b64_tr_b16 v[148:149], v252 offset:45568
	ds_read_b64_tr_b16 v[150:151], v252 offset:47616
	v_fmamk_f32 v65, v185, 0x42040000, v187
	v_fmamk_f32 v66, v185, 0x42080000, v187
	v_fmamk_f32 v67, v185, 0x420c0000, v187
	v_fmamk_f32 v68, v185, 0x42200000, v187
	v_fmamk_f32 v69, v185, 0x42240000, v187
	v_fmamk_f32 v70, v185, 0x42280000, v187
	s_waitcnt lgkmcnt(6)
	v_mfma_f32_32x32x16_bf16 v[16:31], v[136:139], v[152:155], v[16:31]
	ds_read_b64_tr_b16 v[152:153], v252 offset:46080
	ds_read_b64_tr_b16 v[154:155], v252 offset:48128
	v_fmamk_f32 v71, v185, 0x422c0000, v187
	v_fmamk_f32 v72, v185, 0x42400000, v187
	v_fmamk_f32 v73, v185, 0x42440000, v187
	v_fmamk_f32 v74, v185, 0x42480000, v187
	v_fmamk_f32 v75, v185, 0x424c0000, v187
	v_fmamk_f32 v76, v185, 0x42600000, v187
	s_waitcnt lgkmcnt(6)
	v_mfma_f32_32x32x16_bf16 v[0:15], v[136:139], v[156:159], v[0:15]
	ds_read_b64_tr_b16 v[156:157], v252 offset:46592
	ds_read_b64_tr_b16 v[158:159], v252 offset:48640
	v_fmamk_f32 v77, v185, 0x42640000, v187
	v_fmamk_f32 v78, v185, 0x42680000, v187
	v_fmamk_f32 v79, v185, 0x426c0000, v187
	v_exp_f32_e32 v112, v112
	v_exp_f32_e32 v113, v113
	s_waitcnt lgkmcnt(6)
	v_mfma_f32_32x32x16_bf16 v[48:63], v[140:143], v[144:147], v[48:63]
	ds_read_b64_tr_b16 v[144:145], v252 offset:49152
	ds_read_b64_tr_b16 v[146:147], v252 offset:51200
	v_exp_f32_e32 v114, v114
	v_exp_f32_e32 v115, v115
	v_add_f32_e32 v182, v112, v182
	v_add_f32_e32 v182, v113, v182
	s_waitcnt lgkmcnt(6)
	v_mfma_f32_32x32x16_bf16 v[32:47], v[140:143], v[148:151], v[32:47]
	ds_read_b64_tr_b16 v[148:149], v252 offset:49664
	ds_read_b64_tr_b16 v[150:151], v252 offset:51712
	v_cvt_pk_bf16_f32 v128, v112, v113
	v_exp_f32_e32 v116, v116
	v_exp_f32_e32 v117, v117
	v_add_f32_e32 v182, v114, v182
	s_waitcnt lgkmcnt(6)
	v_mfma_f32_32x32x16_bf16 v[16:31], v[140:143], v[152:155], v[16:31]
	ds_read_b64_tr_b16 v[152:153], v252 offset:50176
	ds_read_b64_tr_b16 v[154:155], v252 offset:52224
	v_add_f32_e32 v182, v115, v182
	v_cvt_pk_bf16_f32 v129, v114, v115
	v_exp_f32_e32 v118, v118
	v_exp_f32_e32 v119, v119
	s_waitcnt lgkmcnt(6)
	v_mfma_f32_32x32x16_bf16 v[0:15], v[140:143], v[156:159], v[0:15]
	ds_read_b64_tr_b16 v[156:157], v252 offset:50688
	ds_read_b64_tr_b16 v[158:159], v252 offset:52736
	v_add_f32_e32 v182, v116, v182
	v_add_f32_e32 v182, v117, v182
	v_cvt_pk_bf16_f32 v130, v116, v117
	v_cvt_pk_bf16_f32 v131, v118, v119
	v_add_f32_e32 v182, v118, v182
	v_add_f32_e32 v182, v119, v182
	s_add_i32 s100, s55, 62
	s_cmp_lt_u32 s100, 93
	s_cbranch_scc0 .Lsym_nodiag_s2
	v_add_f32_e32 v190, 0x00000000, v183
	v_add_f32_e32 v191, 0xc2000000, v183
	v_fma_f32 v80, |v190|, v186, s16
	v_fma_f32 v64, |v191|, v186, s16
	v_add_f32_e32 v190, 0xbf800000, v183
	v_add_f32_e32 v191, 0xc2040000, v183
	v_fma_f32 v81, |v190|, v186, s16
	v_fma_f32 v65, |v191|, v186, s16
	v_add_f32_e32 v190, 0xc0000000, v183
	v_add_f32_e32 v191, 0xc2080000, v183
	v_fma_f32 v82, |v190|, v186, s16
	v_fma_f32 v66, |v191|, v186, s16
	v_add_f32_e32 v190, 0xc0400000, v183
	v_add_f32_e32 v191, 0xc20c0000, v183
	v_fma_f32 v83, |v190|, v186, s16
	v_fma_f32 v67, |v191|, v186, s16
	v_add_f32_e32 v190, 0xc1000000, v183
	v_add_f32_e32 v191, 0xc2200000, v183
	v_fma_f32 v84, |v190|, v186, s16
	v_fma_f32 v68, |v191|, v186, s16
	v_add_f32_e32 v190, 0xc1100000, v183
	v_add_f32_e32 v191, 0xc2240000, v183
	v_fma_f32 v85, |v190|, v186, s16
	v_fma_f32 v69, |v191|, v186, s16
	v_add_f32_e32 v190, 0xc1200000, v183
	v_add_f32_e32 v191, 0xc2280000, v183
	v_fma_f32 v86, |v190|, v186, s16
	v_fma_f32 v70, |v191|, v186, s16
	v_add_f32_e32 v190, 0xc1300000, v183
	v_add_f32_e32 v191, 0xc22c0000, v183
	v_fma_f32 v87, |v190|, v186, s16
	v_fma_f32 v71, |v191|, v186, s16
	v_add_f32_e32 v190, 0xc1800000, v183
	v_add_f32_e32 v191, 0xc2400000, v183
	v_fma_f32 v88, |v190|, v186, s16
	v_fma_f32 v72, |v191|, v186, s16
	v_add_f32_e32 v190, 0xc1880000, v183
	v_add_f32_e32 v191, 0xc2440000, v183
	v_fma_f32 v89, |v190|, v186, s16
	v_fma_f32 v73, |v191|, v186, s16
	v_add_f32_e32 v190, 0xc1900000, v183
	v_add_f32_e32 v191, 0xc2480000, v183
	v_fma_f32 v90, |v190|, v186, s16
	v_fma_f32 v74, |v191|, v186, s16
	v_add_f32_e32 v190, 0xc1980000, v183
	v_add_f32_e32 v191, 0xc24c0000, v183
	v_fma_f32 v91, |v190|, v186, s16
	v_fma_f32 v75, |v191|, v186, s16
	v_add_f32_e32 v190, 0xc1c00000, v183
	v_add_f32_e32 v191, 0xc2600000, v183
	v_fma_f32 v92, |v190|, v186, s16
	v_fma_f32 v76, |v191|, v186, s16
	v_add_f32_e32 v190, 0xc1c80000, v183
	v_add_f32_e32 v191, 0xc2640000, v183
	v_fma_f32 v93, |v190|, v186, s16
	v_fma_f32 v77, |v191|, v186, s16
	v_add_f32_e32 v190, 0xc1d00000, v183
	v_add_f32_e32 v191, 0xc2680000, v183
	v_fma_f32 v94, |v190|, v186, s16
	v_fma_f32 v78, |v191|, v186, s16
	v_add_f32_e32 v190, 0xc1d80000, v183
	v_add_f32_e32 v191, 0xc26c0000, v183
	v_fma_f32 v95, |v190|, v186, s16
	v_fma_f32 v79, |v191|, v186, s16

; template <int KS> __device__ __forceinline__ void pv_ks(f32x16* o, int vb, bf16x8 pa) {
;     const s16x4 l0 = tr_read<v_rd_off(0, KS, 0)>(vb), h0 = tr_read<v_rd_off(0, KS, 1)>(vb), l1 = tr_read<v_rd_off(1, KS, 0)>(vb), h1 = tr_read<v_rd_off(1, KS, 1)>(vb);
;     const s16x4 l2 = tr_read<v_rd_off(2, KS, 0)>(vb), h2 = tr_read<v_rd_off(2, KS, 1)>(vb), l3 = tr_read<v_rd_off(3, KS, 0)>(vb), h3 = tr_read<v_rd_off(3, KS, 1)>(vb);
;     ...
;     asm volatile("s_waitcnt lgkmcnt(6)" ::: "memory"); SBAR();
;     o[0] = __builtin_amdgcn_mfma_f32_32x32x16_bf16(pa, PK(l0, h0), o[0], 0, 0, 0);
;     asm volatile("s_waitcnt lgkmcnt(4)" ::: "memory"); SBAR();
;     o[1] = __builtin_amdgcn_mfma_f32_32x32x16_bf16(pa, PK(l1, h1), o[1], 0, 0, 0);
;     asm volatile("s_waitcnt lgkmcnt(2)" ::: "memory"); SBAR();
;     o[2] = __builtin_amdgcn_mfma_f32_32x32x16_bf16(pa, PK(l2, h2), o[2], 0, 0, 0);
;     asm volatile("s_waitcnt lgkmcnt(0)" ::: "memory"); SBAR();
;     o[3] = __builtin_amdgcn_mfma_f32_32x32x16_bf16(pa, PK(l3, h3), o[3], 0, 0, 0);
;     ...
; }
; __device__ __forceinline__ void pv_d0(f32x16* o, int vb, bf16x8 pa0, bf16x8 pa1, bf16x8 pa2, bf16x8 pa3) {
;     __builtin_amdgcn_s_setprio(1);
;     pv_ks<0>(o, vb, pa0); pv_ks<1>(o, vb, pa1); pv_ks<2>(o, vb, pa2); pv_ks<3>(o, vb, pa3);
;     __builtin_amdgcn_s_setprio(0);
; }
; __device__ __forceinline__ void exp_half(f32x16& p) {
; #pragma unroll
;     for (int r = 0; r < 16; ++r) p[r] = __builtin_amdgcn_exp2f(p[r]);
; }
; __device__ __forceinline__ void pack_p(const f32x16& p0, const f32x16& p1, float& l_reg, bf16x8& pa0, bf16x8& pa1, bf16x8& pa2, bf16x8& pa3) {
;     float ps = 0;
; #pragma unroll
;     for (int r = 0; r < 16; ++r) ps += p0[r];
; #pragma unroll
;     for (int r = 0; r < 16; ++r) ps += p1[r];
;     l_reg += ps;
;     ...
;     PK4(p0, 0, pa0); PK4(p0, 8, pa1); PK4(p1, 0, pa2); PK4(p1, 8, pa3);
;     ...
; }
; template <int ND0> __device__ __forceinline__ void qkt(f32x16& p0, f32x16& p1, const char* Ks, const bf16x8* qr, int r32, int hi, int colB0) {
; #pragma unroll
;     for (int d0 = 0; d0 < ND0; ++d0) { const int cb = colB0 + (d0 * 16 + hi * 8) * 2;
;         const bf16x8 b0 = *reinterpret_cast<const bf16x8*>(Ks + KSWZ(r32, cb));
;         const bf16x8 b1 = *reinterpret_cast<const bf16x8*>(Ks + KSWZ(32 + r32, cb));
;         p0 = __builtin_amdgcn_mfma_f32_32x32x16_bf16(b0, qr[d0], p0, 0, 0, 0);
.Lsym_nostage_s3:
	s_waitcnt lgkmcnt(14)
	v_mfma_f32_32x32x16_bf16 v[48:63], v[128:131], v[144:147], v[48:63]
	ds_read_b64_tr_b16 v[144:145], v252 offset:53248
	ds_read_b64_tr_b16 v[146:147], v252 offset:55296
	v_exp_f32_e32 v120, v120
	v_exp_f32_e32 v121, v121
	v_exp_f32_e32 v122, v122
	s_waitcnt lgkmcnt(14)
	v_mfma_f32_32x32x16_bf16 v[32:47], v[128:131], v[148:151], v[32:47]
	ds_read_b64_tr_b16 v[148:149], v252 offset:53760
	ds_read_b64_tr_b16 v[150:151], v252 offset:55808
	v_exp_f32_e32 v123, v123
	v_add_f32_e32 v182, v120, v182
	v_add_f32_e32 v182, v121, v182
	v_cvt_pk_bf16_f32 v132, v120, v121
	v_exp_f32_e32 v124, v124
	s_waitcnt lgkmcnt(14)
	v_mfma_f32_32x32x16_bf16 v[16:31], v[128:131], v[152:155], v[16:31]
	ds_read_b64_tr_b16 v[152:153], v252 offset:54272
	ds_read_b64_tr_b16 v[154:155], v252 offset:56320
	v_exp_f32_e32 v125, v125
	v_add_f32_e32 v182, v122, v182
	v_add_f32_e32 v182, v123, v182
	v_cvt_pk_bf16_f32 v133, v122, v123
	s_waitcnt lgkmcnt(13)
	v_mfma_f32_32x32x16_bf16 v[80:95], v[192:195], v[172:175], v[80:95]
	v_exp_f32_e32 v126, v126
	v_exp_f32_e32 v127, v127
	v_add_f32_e32 v182, v124, v182
	v_add_f32_e32 v182, v125, v182
	v_mfma_f32_32x32x16_bf16 v[0:15], v[128:131], v[156:159], v[0:15]
	ds_read_b64_tr_b16 v[156:157], v252 offset:54784
	ds_read_b64_tr_b16 v[158:159], v252 offset:56832
	v_cvt_pk_bf16_f32 v134, v124, v125
	v_cvt_pk_bf16_f32 v135, v126, v127
	v_add_f32_e32 v182, v126, v182
	v_add_f32_e32 v182, v127, v182
	v_exp_f32_e32 v96, v96
	s_waitcnt lgkmcnt(14)
	v_mfma_f32_32x32x16_bf16 v[64:79], v[196:199], v[172:175], v[64:79]
	v_exp_f32_e32 v97, v97
	v_exp_f32_e32 v98, v98
	v_exp_f32_e32 v99, v99
	v_add_f32_e32 v182, v96, v182
	s_waitcnt lgkmcnt(6)
	v_mfma_f32_32x32x16_bf16 v[48:63], v[132:135], v[144:147], v[48:63]
	ds_read_b64_tr_b16 v[144:145], v252 offset:57344
	ds_read_b64_tr_b16 v[146:147], v252 offset:59392
	v_add_f32_e32 v182, v97, v182
	v_cvt_pk_bf16_f32 v136, v96, v97
	v_exp_f32_e32 v100, v100
	v_exp_f32_e32 v101, v101
	v_mfma_f32_32x32x16_bf16 v[80:95], v[200:203], v[168:171], v[80:95]
	v_add_f32_e32 v182, v98, v182
	v_add_f32_e32 v182, v99, v182
	v_cvt_pk_bf16_f32 v137, v98, v99
	v_exp_f32_e32 v102, v102
	s_waitcnt lgkmcnt(6)
	v_mfma_f32_32x32x16_bf16 v[32:47], v[132:135], v[148:151], v[32:47]
	ds_read_b64_tr_b16 v[148:149], v252 offset:57856
	ds_read_b64_tr_b16 v[150:151], v252 offset:59904
	v_exp_f32_e32 v103, v103
	v_add_f32_e32 v182, v100, v182
	v_add_f32_e32 v182, v101, v182
	v_cvt_pk_bf16_f32 v138, v100, v101
	v_cvt_pk_bf16_f32 v139, v102, v103
	v_add_f32_e32 v182, v102, v182
	v_mfma_f32_32x32x16_bf16 v[64:79], v[204:207], v[168:171], v[64:79]
	v_add_f32_e32 v182, v103, v182
	v_exp_f32_e32 v104, v104
	v_exp_f32_e32 v105, v105
	v_exp_f32_e32 v106, v106
	s_waitcnt lgkmcnt(6)
	v_mfma_f32_32x32x16_bf16 v[16:31], v[132:135], v[152:155], v[16:31]
	ds_read_b64_tr_b16 v[152:153], v252 offset:58368
	ds_read_b64_tr_b16 v[154:155], v252 offset:60416
	v_exp_f32_e32 v107, v107
	v_add_f32_e32 v182, v104, v182
	v_add_f32_e32 v182, v105, v182
	v_cvt_pk_bf16_f32 v140, v104, v105
	v_mfma_f32_32x32x16_bf16 v[80:95], v[208:211], v[164:167], v[80:95]
	v_exp_f32_e32 v108, v108
	v_exp_f32_e32 v109, v109
	v_add_f32_e32 v182, v106, v182
	v_add_f32_e32 v182, v107, v182
	s_waitcnt lgkmcnt(6)
	v_mfma_f32_32x32x16_bf16 v[0:15], v[132:135], v[156:159], v[0:15]
	ds_read_b64_tr_b16 v[156:157], v252 offset:58880
	ds_read_b64_tr_b16 v[158:159], v252 offset:60928
	v_cvt_pk_bf16_f32 v141, v106, v107
	v_exp_f32_e32 v110, v110
	v_exp_f32_e32 v111, v111
	v_add_f32_e32 v182, v108, v182
	v_mfma_f32_32x32x16_bf16 v[64:79], v[212:215], v[164:167], v[64:79]
	v_add_f32_e32 v182, v109, v182
	v_cvt_pk_bf16_f32 v142, v108, v109
	v_cvt_pk_bf16_f32 v143, v110, v111
	v_add_f32_e32 v182, v110, v182
	v_add_f32_e32 v182, v111, v182
	s_cmp_lt_i32 s55, 0
	s_cselect_b32 s100, -1.0, 1.0
	v_mul_f32_e32 v185, s100, v186
	v_mfma_f32_32x32x16_bf16 v[80:95], v[216:219], v[160:163], v[80:95]
	v_fma_f32 v187, -v185, v183, s16
	v_fmamk_f32 v112, v185, 0x00000000, v187
	v_fmamk_f32 v113, v185, 0x3f800000, v187
	v_fmamk_f32 v114, v185, 0x40000000, v187
	v_fmamk_f32 v115, v185, 0x40400000, v187
	v_fmamk_f32 v116, v185, 0x41000000, v187
	v_mfma_f32_32x32x16_bf16 v[64:79], v[220:223], v[160:163], v[64:79]
	v_fmamk_f32 v117, v185, 0x41100000, v187
	v_fmamk_f32 v118, v185, 0x41200000, v187
	v_fmamk_f32 v119, v185, 0x41300000, v187
	v_fmamk_f32 v120, v185, 0x41800000, v187
	v_fmamk_f32 v121, v185, 0x41880000, v187
	v_fmamk_f32 v122, v185, 0x41900000, v187
	s_waitcnt lgkmcnt(6)
	v_mfma_f32_32x32x16_bf16 v[48:63], v[136:139], v[144:147], v[48:63]
	ds_read_b64_tr_b16 v[144:145], v252 offset:61440
	ds_read_b64_tr_b16 v[146:147], v252 offset:63488
	v_fmamk_f32 v123, v185, 0x41980000, v187
	v_fmamk_f32 v124, v185, 0x41c00000, v187
	v_fmamk_f32 v125, v185, 0x41c80000, v187
	v_fmamk_f32 v126, v185, 0x41d00000, v187
	v_fmamk_f32 v127, v185, 0x41d80000, v187
	v_fmamk_f32 v96, v185, 0x42000000, v187
	s_waitcnt lgkmcnt(6)
; template <int KS> __device__ __forceinline__ void pv_ks(f32x16* o, int vb, bf16x8 pa) {
;     const s16x4 l0 = tr_read<v_rd_off(0, KS, 0)>(vb), h0 = tr_read<v_rd_off(0, KS, 1)>(vb), l1 = tr_read<v_rd_off(1, KS, 0)>(vb), h1 = tr_read<v_rd_off(1, KS, 1)>(vb);
;     const s16x4 l2 = tr_read<v_rd_off(2, KS, 0)>(vb), h2 = tr_read<v_rd_off(2, KS, 1)>(vb), l3 = tr_read<v_rd_off(3, KS, 0)>(vb), h3 = tr_read<v_rd_off(3, KS, 1)>(vb);
;     ...
;     asm volatile("s_waitcnt lgkmcnt(6)" ::: "memory"); SBAR();
;     o[0] = __builtin_amdgcn_mfma_f32_32x32x16_bf16(pa, PK(l0, h0), o[0], 0, 0, 0);
;     asm volatile("s_waitcnt lgkmcnt(4)" ::: "memory"); SBAR();
;     o[1] = __builtin_amdgcn_mfma_f32_32x32x16_bf16(pa, PK(l1, h1), o[1], 0, 0, 0);
;     asm volatile("s_waitcnt lgkmcnt(2)" ::: "memory"); SBAR();
;     o[2] = __builtin_amdgcn_mfma_f32_32x32x16_bf16(pa, PK(l2, h2), o[2], 0, 0, 0);
;     asm volatile("s_waitcnt lgkmcnt(0)" ::: "memory"); SBAR();
;     o[3] = __builtin_amdgcn_mfma_f32_32x32x16_bf16(pa, PK(l3, h3), o[3], 0, 0, 0);
;     ...
; }
; __device__ __forceinline__ void pv_d0(f32x16* o, int vb, bf16x8 pa0, bf16x8 pa1, bf16x8 pa2, bf16x8 pa3) {
;     __builtin_amdgcn_s_setprio(1);
;     pv_ks<0>(o, vb, pa0); pv_ks<1>(o, vb, pa1); pv_ks<2>(o, vb, pa2); pv_ks<3>(o, vb, pa3);
;     __builtin_amdgcn_s_setprio(0);
; }
; __device__ __forceinline__ void exp_half(f32x16& p) {
; #pragma unroll
;     for (int r = 0; r < 16; ++r) p[r] = __builtin_amdgcn_exp2f(p[r]);
; }
; __device__ __forceinline__ void pack_p(const f32x16& p0, const f32x16& p1, float& l_reg, bf16x8& pa0, bf16x8& pa1, bf16x8& pa2, bf16x8& pa3) {
;     float ps = 0;
; #pragma unroll
;     for (int r = 0; r < 16; ++r) ps += p0[r];
; #pragma unroll
;     for (int r = 0; r < 16; ++r) ps += p1[r];
;     l_reg += ps;
;     ...
;     PK4(p0, 0, pa0); PK4(p0, 8, pa1); PK4(p1, 0, pa2); PK4(p1, 8, pa3);
;     ...
; }
; template <int ND0> __device__ __forceinline__ void qkt(f32x16& p0, f32x16& p1, const char* Ks, const bf16x8* qr, int r32, int hi, int colB0) {
; #pragma unroll
;     for (int d0 = 0; d0 < ND0; ++d0) { const int cb = colB0 + (d0 * 16 + hi * 8) * 2;
;         const bf16x8 b0 = *reinterpret_cast<const bf16x8*>(Ks + KSWZ(r32, cb));
;         const bf16x8 b1 = *reinterpret_cast<const bf16x8*>(Ks + KSWZ(32 + r32, cb));
;         p0 = __builtin_amdgcn_mfma_f32_32x32x16_bf16(b0, qr[d0], p0, 0, 0, 0);
	v_mfma_f32_32x32x16_bf16 v[32:47], v[136:139], v[148:151], v[32:47]
	ds_read_b64_tr_b16 v[148:149], v252 offset:61952
	ds_read_b64_tr_b16 v[150:151], v252 offset:64000
	v_fmamk_f32 v97, v185, 0x42040000, v187
	v_fmamk_f32 v98, v185, 0x42080000, v187
	v_fmamk_f32 v99, v185, 0x420c0000, v187
	v_fmamk_f32 v100, v185, 0x42200000, v187
	v_fmamk_f32 v101, v185, 0x42240000, v187
	v_fmamk_f32 v102, v185, 0x42280000, v187
	s_waitcnt lgkmcnt(6)
	v_mfma_f32_32x32x16_bf16 v[16:31], v[136:139], v[152:155], v[16:31]
	ds_read_b64_tr_b16 v[152:153], v252 offset:62464
	ds_read_b64_tr_b16 v[154:155], v252 offset:64512
	v_fmamk_f32 v103, v185, 0x422c0000, v187
	v_fmamk_f32 v104, v185, 0x42400000, v187
	v_fmamk_f32 v105, v185, 0x42440000, v187
	v_fmamk_f32 v106, v185, 0x42480000, v187
	v_fmamk_f32 v107, v185, 0x424c0000, v187
	v_fmamk_f32 v108, v185, 0x42600000, v187
	s_waitcnt lgkmcnt(6)
	v_mfma_f32_32x32x16_bf16 v[0:15], v[136:139], v[156:159], v[0:15]
	ds_read_b64_tr_b16 v[156:157], v252 offset:62976
	ds_read_b64_tr_b16 v[158:159], v252 offset:65024
	v_fmamk_f32 v109, v185, 0x42640000, v187
	v_fmamk_f32 v110, v185, 0x42680000, v187
	v_fmamk_f32 v111, v185, 0x426c0000, v187
	v_exp_f32_e32 v80, v80
	v_exp_f32_e32 v81, v81
	s_waitcnt lgkmcnt(6)
	v_mfma_f32_32x32x16_bf16 v[48:63], v[140:143], v[144:147], v[48:63]
	ds_read_b64_tr_b16 v[144:145], v252 offset:0
	ds_read_b64_tr_b16 v[146:147], v252 offset:2048
	v_exp_f32_e32 v82, v82
	v_exp_f32_e32 v83, v83
	v_add_f32_e32 v182, v80, v182
	v_add_f32_e32 v182, v81, v182
	s_waitcnt lgkmcnt(6)
	v_mfma_f32_32x32x16_bf16 v[32:47], v[140:143], v[148:151], v[32:47]
	ds_read_b64_tr_b16 v[148:149], v252 offset:512
	ds_read_b64_tr_b16 v[150:151], v252 offset:2560
	v_cvt_pk_bf16_f32 v128, v80, v81
	v_exp_f32_e32 v84, v84
	v_exp_f32_e32 v85, v85
	v_add_f32_e32 v182, v82, v182
	s_waitcnt lgkmcnt(6)
	v_mfma_f32_32x32x16_bf16 v[16:31], v[140:143], v[152:155], v[16:31]
	ds_read_b64_tr_b16 v[152:153], v252 offset:1024
	ds_read_b64_tr_b16 v[154:155], v252 offset:3072
	v_add_f32_e32 v182, v83, v182
	v_cvt_pk_bf16_f32 v129, v82, v83
	v_exp_f32_e32 v86, v86
	v_exp_f32_e32 v87, v87
	s_waitcnt lgkmcnt(6)
	v_mfma_f32_32x32x16_bf16 v[0:15], v[140:143], v[156:159], v[0:15]
	ds_read_b64_tr_b16 v[156:157], v252 offset:1536
	ds_read_b64_tr_b16 v[158:159], v252 offset:3584
	v_add_f32_e32 v182, v84, v182
	v_add_f32_e32 v182, v85, v182
	v_cvt_pk_bf16_f32 v130, v84, v85
	v_cvt_pk_bf16_f32 v131, v86, v87
	v_add_f32_e32 v182, v86, v182
	v_add_f32_e32 v182, v87, v182
	s_add_i32 s100, s55, 62
	s_cmp_lt_u32 s100, 93
	s_cbranch_scc0 .Lsym_nodiag_s3
	v_add_f32_e32 v190, 0x00000000, v183
	v_add_f32_e32 v191, 0xc2000000, v183
	v_fma_f32 v112, |v190|, v186, s16
	v_fma_f32 v96, |v191|, v186, s16
	v_add_f32_e32 v190, 0xbf800000, v183
	v_add_f32_e32 v191, 0xc2040000, v183
	v_fma_f32 v113, |v190|, v186, s16
	v_fma_f32 v97, |v191|, v186, s16
	v_add_f32_e32 v190, 0xc0000000, v183
	v_add_f32_e32 v191, 0xc2080000, v183
	v_fma_f32 v114, |v190|, v186, s16
	v_fma_f32 v98, |v191|, v186, s16
	v_add_f32_e32 v190, 0xc0400000, v183
	v_add_f32_e32 v191, 0xc20c0000, v183
	v_fma_f32 v115, |v190|, v186, s16
	v_fma_f32 v99, |v191|, v186, s16
	v_add_f32_e32 v190, 0xc1000000, v183
	v_add_f32_e32 v191, 0xc2200000, v183
	v_fma_f32 v116, |v190|, v186, s16
	v_fma_f32 v100, |v191|, v186, s16
	v_add_f32_e32 v190, 0xc1100000, v183
	v_add_f32_e32 v191, 0xc2240000, v183
	v_fma_f32 v117, |v190|, v186, s16
	v_fma_f32 v101, |v191|, v186, s16
	v_add_f32_e32 v190, 0xc1200000, v183
	v_add_f32_e32 v191, 0xc2280000, v183
	v_fma_f32 v118, |v190|, v186, s16
	v_fma_f32 v102, |v191|, v186, s16
	v_add_f32_e32 v190, 0xc1300000, v183
	v_add_f32_e32 v191, 0xc22c0000, v183
	v_fma_f32 v119, |v190|, v186, s16
	v_fma_f32 v103, |v191|, v186, s16
	v_add_f32_e32 v190, 0xc1800000, v183
	v_add_f32_e32 v191, 0xc2400000, v183
	v_fma_f32 v120, |v190|, v186, s16
	v_fma_f32 v104, |v191|, v186, s16
	v_add_f32_e32 v190, 0xc1880000, v183
	v_add_f32_e32 v191, 0xc2440000, v183
	v_fma_f32 v121, |v190|, v186, s16
	v_fma_f32 v105, |v191|, v186, s16
	v_add_f32_e32 v190, 0xc1900000, v183
	v_add_f32_e32 v191, 0xc2480000, v183
	v_fma_f32 v122, |v190|, v186, s16
	v_fma_f32 v106, |v191|, v186, s16
	v_add_f32_e32 v190, 0xc1980000, v183
	v_add_f32_e32 v191, 0xc24c0000, v183
	v_fma_f32 v123, |v190|, v186, s16
	v_fma_f32 v107, |v191|, v186, s16
	v_add_f32_e32 v190, 0xc1c00000, v183
	v_add_f32_e32 v191, 0xc2600000, v183
	v_fma_f32 v124, |v190|, v186, s16
	v_fma_f32 v108, |v191|, v186, s16
	v_add_f32_e32 v190, 0xc1c80000, v183
	v_add_f32_e32 v191, 0xc2640000, v183
	v_fma_f32 v125, |v190|, v186, s16
	v_fma_f32 v109, |v191|, v186, s16
	v_add_f32_e32 v190, 0xc1d00000, v183
	v_add_f32_e32 v191, 0xc2680000, v183
	v_fma_f32 v126, |v190|, v186, s16
	v_fma_f32 v110, |v191|, v186, s16
	v_add_f32_e32 v190, 0xc1d80000, v183
	v_add_f32_e32 v191, 0xc26c0000, v183
	v_fma_f32 v127, |v190|, v186, s16
	v_fma_f32 v111, |v191|, v186, s16
